# stack: scan D1/S-prime reads batched, scan chunk-end barrier dropped, GEMM setprio flips removed (on top of attention ring + rw deferred unpack)
# baseline (speedup 1.0000x reference)
; #define LAS __attribute__((address_space(3)))
; DI void scan_phase(unsigned char* sl, int layer, bool ctx_out, bool do_store, LAS unsigned char* lds) {
;     ...
; #pragma unroll
;         for (int t = 0; t < 2; ++t)
; #pragma unroll
;             for (int g = 0; g < 4; ++g) { const int k0 = 32 * (kb0 + t) + 8 * g + 4 * hh; const f32x4 aS = *(const LAS f32x4*)(vec + 128 + k0), bS = *(const LAS f32x4*)(vec + 256 + k0);
; #pragma unroll
;                 for (int e = 0; e < 4; ++e) sacc[t][4 * g + e] = aS[e] * sacc[t][4 * g + e] + bS[e] * d1[t][4 * g + e]; }
;         __syncthreads();
.LBB0_307:
	ds_read_b128 v[34:37], v211
	ds_read_b128 v[38:41], v212
	ds_read_b128 v[42:45], v213
	ds_read_b128 v[46:49], v214
	ds_read_b128 v[50:53], v215
	ds_read_b128 v[54:57], v216
	ds_read_b128 v[58:61], v217
	ds_read_b128 v[62:65], v218
	ds_read_b128 v[66:69], v219
	ds_read_b128 v[70:73], v220
	ds_read_b128 v[74:77], v221
	ds_read_b128 v[78:81], v222
	ds_read_b128 v[82:85], v223
	ds_read_b128 v[86:89], v224
	ds_read_b128 v[90:93], v225
	ds_read_b128 v[94:97], v226
	s_waitcnt lgkmcnt(0)
	v_pk_mul_f32 v[20:21], v[20:21], v[40:41]
	v_pk_mul_f32 v[24:25], v[24:25], v[48:49]
	v_pk_mul_f32 v[28:29], v[28:29], v[56:57]
	v_pk_mul_f32 v[32:33], v[32:33], v[64:65]
	v_pk_mul_f32 v[18:19], v[18:19], v[38:39]
	v_pk_mul_f32 v[22:23], v[22:23], v[46:47]
	v_pk_mul_f32 v[26:27], v[26:27], v[54:55]
	v_pk_mul_f32 v[30:31], v[30:31], v[62:63]
	v_pk_mul_f32 v[4:5], v[4:5], v[72:73]
	v_pk_mul_f32 v[8:9], v[8:9], v[80:81]
	v_pk_mul_f32 v[12:13], v[12:13], v[88:89]
	v_pk_mul_f32 v[16:17], v[16:17], v[96:97]
	v_pk_mul_f32 v[2:3], v[2:3], v[70:71]
	v_pk_mul_f32 v[6:7], v[6:7], v[78:79]
	v_pk_mul_f32 v[10:11], v[10:11], v[86:87]
	v_pk_mul_f32 v[14:15], v[14:15], v[94:95]
	s_add_i32 s92, s92, -1
	v_pk_fma_f32 v[150:151], v[150:151], v[92:93], v[16:17]
	v_pk_fma_f32 v[148:149], v[148:149], v[90:91], v[14:15]
	v_pk_fma_f32 v[146:147], v[146:147], v[84:85], v[12:13]
	v_pk_fma_f32 v[144:145], v[144:145], v[82:83], v[10:11]
	v_pk_fma_f32 v[142:143], v[142:143], v[76:77], v[8:9]
	v_pk_fma_f32 v[140:141], v[140:141], v[74:75], v[6:7]
	v_pk_fma_f32 v[138:139], v[138:139], v[68:69], v[4:5]
	v_pk_fma_f32 v[136:137], v[136:137], v[66:67], v[2:3]
	v_pk_fma_f32 v[134:135], v[134:135], v[60:61], v[32:33]
	v_pk_fma_f32 v[132:133], v[132:133], v[58:59], v[30:31]
	v_pk_fma_f32 v[130:131], v[130:131], v[52:53], v[28:29]
	v_pk_fma_f32 v[128:129], v[128:129], v[50:51], v[26:27]
	v_pk_fma_f32 v[126:127], v[126:127], v[44:45], v[24:25]
	v_pk_fma_f32 v[124:125], v[124:125], v[42:43], v[22:23]
	v_pk_fma_f32 v[122:123], v[122:123], v[36:37], v[20:21]
	v_pk_fma_f32 v[120:121], v[120:121], v[34:35], v[18:19]
	s_cmpk_lg_i32 s70, 0x44
	s_mov_b32 s69, s70
	s_nop 0
	s_cbranch_scc0 .LBB0_323

; DI void scan_phase(unsigned char* sl, int layer, bool ctx_out, bool do_store, LAS unsigned char* lds) {
;     ...
;         __syncthreads();
; #pragma unroll
;         for (int t = 0; t < 2; ++t)
; #pragma unroll
;             for (int g = 0; g < 4; ++g) { const int k0 = 32 * (kb0 + t) + 8 * g + 4 * hh; const f32x4 ea = *(const LAS f32x4*)(vec + k0);
;                 u32x2 w; w.x = cvtpk(sacc[t][4 * g] * ea[0], sacc[t][4 * g + 1] * ea[1]); w.y = cvtpk(sacc[t][4 * g + 2] * ea[2], sacc[t][4 * g + 3] * ea[3]);
;                 *(LAS u32x2*)(lds + SC_ST + (32 * vb + r32) * 272 + k0 * 2) = w; }
;         __syncthreads();
;         f32x16 d1[2];
; #pragma unroll
;         for (int t = 0; t < 2; ++t) {
; #pragma unroll
;             for (int i = 0; i < 16; ++i) d1[t][i] = 0.f;
; #pragma unroll
;             for (int s = 0; s < 4; ++s) { const bf16x8 af = *(const LAS bf16x8*)(lds + SC_KT + (32 * (kb0 + t) + r32) * 144 + (16 * s + 8 * hh) * 2);
;                 const bf16x8 bfv = *(const LAS bf16x8*)(lds + SC_VT + (32 * vb + r32) * 144 + (16 * s + 8 * hh) * 2);
;                 d1[t] = MFMA32(af, bfv, d1[t]); }
;         }
;         if (need_out) {
;             f32x16 o, p0, p1;
; #pragma unroll
;             for (int i = 0; i < 16; ++i) { o[i] = 0.f; p0[i] = 0.f; p1[i] = 0.f; }
;             bf16x8 qf[8];
; #pragma unroll
;             for (int s = 0; s < 8; ++s) qf[s] = *(const LAS bf16x8*)(lds + SC_QH + (32 * tb + r32) * 272 + (16 * s + 8 * hh) * 2);
;             if (tb == 1) {
; #pragma unroll
;                 for (int s = 0; s < 8; ++s) { const bf16x8 sf = *(const LAS bf16x8*)(lds + SC_ST + (32 * vb + r32) * 272 + (16 * s + 8 * hh) * 2);
;                     const bf16x8 k0 = *(const LAS bf16x8*)(lds + SC_KH + r32 * 272 + (16 * s + 8 * hh) * 2), k1 = *(const LAS bf16x8*)(lds + SC_KH + (32 + r32) * 272 + (16 * s + 8 * hh) * 2);
;                     o = MFMA32(sf, qf[s], o); p0 = MFMA32(k0, qf[s], p0); p1 = MFMA32(k1, qf[s], p1); }
; #pragma unroll
;                 for (int i = 0; i < 16; ++i) if (crow(i, hh) > r32) p1[i] = 0.f;
;             } else {
; #pragma unroll
;                 for (int s = 0; s < 8; ++s) { const bf16x8 sf = *(const LAS bf16x8*)(lds + SC_ST + (32 * vb + r32) * 272 + (16 * s + 8 * hh) * 2);
;                     const bf16x8 k0 = *(const LAS bf16x8*)(lds + SC_KH + r32 * 272 + (16 * s + 8 * hh) * 2);
.LBB0_316:
	s_waitcnt lgkmcnt(0)
	s_barrier
	ds_read_b128 v[44:47], v193
	ds_read_b128 v[48:51], v195
	ds_read_b128 v[52:55], v196
	ds_read_b128 v[56:59], v197
	ds_read_b128 v[60:63], v198
	ds_read_b128 v[64:67], v200
	ds_read_b128 v[68:71], v202
	ds_read_b128 v[72:75], v203
	v_add_u32_e32 v42, v173, v172
	s_and_b64 s[64:65], s[8:9], s[64:65]
	s_and_b64 vcc, exec, s[64:65]
	s_waitcnt lgkmcnt(7)
	v_pk_mul_f32 v[44:45], v[120:121], v[44:45]
	v_pk_mul_f32 v[46:47], v[122:123], v[46:47]
	v_cvt_pk_bf16_f32 v44, v44, v45
	v_cvt_pk_bf16_f32 v45, v46, v47
	ds_write_b64 v232, v[44:45]
	s_waitcnt lgkmcnt(7)
	v_pk_mul_f32 v[48:49], v[124:125], v[48:49]
	v_pk_mul_f32 v[50:51], v[126:127], v[50:51]
	v_cvt_pk_bf16_f32 v48, v48, v49
	v_cvt_pk_bf16_f32 v49, v50, v51
	ds_write_b64 v233, v[48:49]
	s_waitcnt lgkmcnt(7)
	v_pk_mul_f32 v[52:53], v[128:129], v[52:53]
	v_pk_mul_f32 v[54:55], v[130:131], v[54:55]
	v_cvt_pk_bf16_f32 v52, v52, v53
	v_cvt_pk_bf16_f32 v53, v54, v55
	ds_write_b64 v234, v[52:53]
	s_waitcnt lgkmcnt(7)
	v_pk_mul_f32 v[56:57], v[132:133], v[56:57]
	v_pk_mul_f32 v[58:59], v[134:135], v[58:59]
	v_cvt_pk_bf16_f32 v56, v56, v57
	v_cvt_pk_bf16_f32 v57, v58, v59
	ds_write_b64 v235, v[56:57]
	s_waitcnt lgkmcnt(7)
	v_pk_mul_f32 v[60:61], v[136:137], v[60:61]
	v_pk_mul_f32 v[62:63], v[138:139], v[62:63]
	v_cvt_pk_bf16_f32 v60, v60, v61
	v_cvt_pk_bf16_f32 v61, v62, v63
	ds_write_b64 v237, v[60:61]
	s_waitcnt lgkmcnt(7)
	v_pk_mul_f32 v[64:65], v[140:141], v[64:65]
	v_pk_mul_f32 v[66:67], v[142:143], v[66:67]
	v_cvt_pk_bf16_f32 v64, v64, v65
	v_cvt_pk_bf16_f32 v65, v66, v67
	ds_write_b64 v238, v[64:65]
	s_waitcnt lgkmcnt(7)
	v_pk_mul_f32 v[68:69], v[144:145], v[68:69]
	v_pk_mul_f32 v[70:71], v[146:147], v[70:71]
	v_cvt_pk_bf16_f32 v68, v68, v69
	v_cvt_pk_bf16_f32 v69, v70, v71
	ds_write_b64 v239, v[68:69]
	s_waitcnt lgkmcnt(7)
	v_pk_mul_f32 v[72:73], v[148:149], v[72:73]
	v_pk_mul_f32 v[74:75], v[150:151], v[74:75]
	v_cvt_pk_bf16_f32 v72, v72, v73
	v_cvt_pk_bf16_f32 v73, v74, v75
	ds_write_b64 v240, v[72:73]
	s_waitcnt lgkmcnt(0)
	s_barrier
	ds_read_b128 v[44:47], v241 offset:34816
	ds_read_b128 v[76:79], v42 offset:53248
	ds_read_b128 v[60:63], v242 offset:34816
	ds_read_b128 v[48:51], v241 offset:34848
	ds_read_b128 v[80:83], v42 offset:53280
	ds_read_b128 v[64:67], v242 offset:34848
	ds_read_b128 v[52:55], v241 offset:34880
	ds_read_b128 v[84:87], v42 offset:53312
	ds_read_b128 v[68:71], v242 offset:34880
	ds_read_b128 v[56:59], v241 offset:34912
	ds_read_b128 v[88:91], v42 offset:53344
	ds_read_b128 v[72:75], v242 offset:34912
	s_waitcnt lgkmcnt(10)
	v_mfma_f32_32x32x16_bf16 v[18:33], v[44:47], v[76:79], 0
	s_waitcnt lgkmcnt(9)
	v_mfma_f32_32x32x16_bf16 v[2:17], v[60:63], v[76:79], 0
	s_waitcnt lgkmcnt(7)
	v_mfma_f32_32x32x16_bf16 v[18:33], v[48:51], v[80:83], v[18:33]
	s_waitcnt lgkmcnt(6)
	v_mfma_f32_32x32x16_bf16 v[2:17], v[64:67], v[80:83], v[2:17]
	s_waitcnt lgkmcnt(4)
	v_mfma_f32_32x32x16_bf16 v[18:33], v[52:55], v[84:87], v[18:33]
	s_waitcnt lgkmcnt(3)
	v_mfma_f32_32x32x16_bf16 v[2:17], v[68:71], v[84:87], v[2:17]
	s_waitcnt lgkmcnt(1)
	v_mfma_f32_32x32x16_bf16 v[18:33], v[56:59], v[88:91], v[18:33]
	s_waitcnt lgkmcnt(0)
	v_mfma_f32_32x32x16_bf16 v[2:17], v[72:75], v[88:91], v[2:17]
	s_cbranch_vccnz .LBB0_307
	ds_read_b128 v[110:113], v243
	ds_read_b128 v[106:109], v243 offset:32
	ds_read_b128 v[102:105], v243 offset:64
	ds_read_b128 v[98:101], v243 offset:96
	ds_read_b128 v[94:97], v243 offset:128
	ds_read_b128 v[90:93], v243 offset:160
	ds_read_b128 v[86:89], v243 offset:192
	ds_read_b128 v[82:85], v243 offset:224
	v_add_u32_e32 v119, v171, v172
	ds_read_b128 v[66:69], v119
	ds_read_b128 v[114:117], v244 offset:17408
	v_readlane_b32 s64, v254, 53
	v_readlane_b32 s65, v254, 54
	s_andn2_b64 vcc, exec, s[64:65]
	s_mov_b64 s[64:65], -1
	s_cbranch_vccnz .LBB0_319
	s_waitcnt lgkmcnt(0)
	v_mfma_f32_32x32x16_bf16 v[50:65], v[114:117], v[110:113], 0
	ds_read_b128 v[34:37], v244 offset:17440
	ds_read_b128 v[70:73], v119 offset:224
	v_readlane_b32 s64, v254, 47
	v_readlane_b32 s65, v254, 48
	s_waitcnt lgkmcnt(0)
	v_mfma_f32_32x32x16_bf16 v[50:65], v[34:37], v[106:109], v[50:65]
	ds_read_b128 v[34:37], v244 offset:17472
	ds_read_b128 v[38:41], v244 offset:17504
	s_waitcnt lgkmcnt(0)
	v_mfma_f32_32x32x16_bf16 v[50:65], v[34:37], v[102:105], v[50:65]
	v_mfma_f32_32x32x16_bf16 v[50:65], v[38:41], v[98:101], v[50:65]
	ds_read_b128 v[34:37], v244 offset:17536
	ds_read_b128 v[38:41], v244 offset:17568
	s_waitcnt lgkmcnt(0)
	v_mfma_f32_32x32x16_bf16 v[50:65], v[34:37], v[94:97], v[50:65]
	v_mfma_f32_32x32x16_bf16 v[50:65], v[38:41], v[90:93], v[50:65]
	ds_read_b128 v[34:37], v244 offset:17600
	ds_read_b128 v[38:41], v244 offset:17632
	ds_read_b128 v[74:77], v119 offset:32
	ds_read_b128 v[78:81], v119 offset:64
	s_waitcnt lgkmcnt(0)
	v_mfma_f32_32x32x16_bf16 v[50:65], v[34:37], v[86:89], v[50:65]
	v_mfma_f32_32x32x16_bf16 v[50:65], v[38:41], v[82:85], v[50:65]
	v_mfma_f32_32x32x16_bf16 v[34:49], v[66:69], v[110:113], 0
	s_nop 10
	v_cndmask_b32_e64 v182, v50, 0, s[64:65]
	v_readlane_b32 s64, v254, 55
	v_readlane_b32 s65, v254, 56
	v_cndmask_b32_e64 v50, v182, v50, s[60:61]
	v_cndmask_b32_e64 v51, 0, v51, s[60:61]
	v_cndmask_b32_e64 v52, v52, 0, s[64:65]
	v_readlane_b32 s64, v254, 57
	v_mfma_f32_32x32x16_bf16 v[34:49], v[74:77], v[106:109], v[34:49]
	v_readlane_b32 s65, v254, 58
	v_cndmask_b32_e64 v59, v59, 0, s[76:77]
	v_cndmask_b32_e64 v60, v60, 0, s[78:79]
	v_cndmask_b32_e64 v53, v53, 0, s[64:65]
	v_readlane_b32 s64, v254, 59
	v_readlane_b32 s65, v254, 60
	v_cndmask_b32_e64 v61, v61, 0, s[80:81]
	v_mfma_f32_32x32x16_bf16 v[34:49], v[78:81], v[102:105], v[34:49]
	ds_read_b128 v[74:77], v119 offset:96
	ds_read_b128 v[78:81], v119 offset:128
	v_cndmask_b32_e64 v54, v54, 0, s[64:65]
	v_readlane_b32 s64, v254, 61
	v_readlane_b32 s65, v254, 62
	v_cndmask_b32_e64 v62, v62, 0, s[82:83]
	v_cndmask_b32_e64 v63, v63, 0, s[84:85]
	v_cndmask_b32_e64 v55, v55, 0, s[64:65]
	s_waitcnt lgkmcnt(0)
	v_mfma_f32_32x32x16_bf16 v[34:49], v[74:77], v[98:101], v[34:49]
	v_readlane_b32 s64, v254, 63
	v_readlane_b32 s65, v255, 0
	v_cndmask_b32_e64 v64, v64, 0, s[86:87]
	v_cndmask_b32_e64 v65, v65, 0, s[66:67]
	v_cndmask_b32_e64 v56, v56, 0, s[64:65]
	v_readlane_b32 s64, v255, 1
	v_readlane_b32 s65, v255, 2
	v_mfma_f32_32x32x16_bf16 v[34:49], v[78:81], v[94:97], v[34:49]
	ds_read_b128 v[74:77], v119 offset:160
	ds_read_b128 v[78:81], v119 offset:192
	v_cndmask_b32_e64 v57, v57, 0, s[64:65]
	v_readlane_b32 s64, v255, 3
	v_readlane_b32 s65, v255, 4
	s_nop 1
	v_cndmask_b32_e64 v58, v58, 0, s[64:65]
	s_waitcnt lgkmcnt(0)
	v_mfma_f32_32x32x16_bf16 v[34:49], v[74:77], v[90:93], v[34:49]
	s_mov_b64 s[64:65], 0
	v_mfma_f32_32x32x16_bf16 v[34:49], v[78:81], v[86:89], v[34:49]
	v_mfma_f32_32x32x16_bf16 v[34:49], v[70:73], v[82:85], v[34:49]
